# FFN-up K-loops: one s_nop in two load segments so every 16-MFMA block starts 8-byte aligned
# speedup vs baseline: 1.0057x; 1.0011x over previous
.LBB0_1942:
	ds_read_b128 v[130:133], v200
	s_waitcnt lgkmcnt(0)
	ds_read_b128 v[134:137], v200 offset:1024
	ds_read_b128 v[138:141], v200 offset:2048
	ds_read_b128 v[142:145], v200 offset:3072
	ds_read_b128 v[146:149], v201
	ds_read_b128 v[150:153], v201 offset:1024
	ds_read_b128 v[154:157], v201 offset:2048
	ds_read_b128 v[158:161], v201 offset:3072
	s_add_u32 s26, s8, 0xfff80080
	s_addc_u32 s27, s9, -1
	s_cmp_eq_u32 s53, 28
	s_cselect_b32 s29, s7, s27
	s_cselect_b32 s28, s21, s26
	s_cselect_b32 s27, s19, s52
	s_cselect_b32 s26, s50, s51
	v_lshl_add_u64 v[216:217], s[8:9], 0, v[190:191]
	s_add_i32 m0, s35, 0xc000
	ds_read_b128 v[162:165], v202
	ds_read_b128 v[166:169], v202 offset:1024
	ds_read_b128 v[170:173], v202 offset:2048
	ds_read_b128 v[174:177], v202 offset:3072
	ds_read_b128 v[178:181], v202 offset:4096
	ds_read_b128 v[204:207], v202 offset:5120
	ds_read_b128 v[208:211], v202 offset:6144
	ds_read_b128 v[212:215], v202 offset:7168
	global_load_lds_dwordx4 v[216:217], off
	v_lshl_add_u64 v[216:217], s[8:9], 0, v[192:193]
	s_add_i32 m0, s35, 0xe000
	s_nop 0
	global_load_lds_dwordx4 v[216:217], off
	s_waitcnt vmcnt(8)
	s_waitcnt lgkmcnt(0)
	s_barrier
	s_setprio 1
	s_waitcnt lgkmcnt(0)
	v_mfma_f32_16x16x32_bf16 v[126:129], v[130:133], v[162:165], v[126:129]
	v_mfma_f32_16x16x32_bf16 v[122:125], v[138:141], v[162:165], v[122:125]
	v_mfma_f32_16x16x32_bf16 v[118:121], v[130:133], v[170:173], v[118:121]
	v_mfma_f32_16x16x32_bf16 v[110:113], v[138:141], v[170:173], v[110:113]
	v_mfma_f32_16x16x32_bf16 v[102:105], v[130:133], v[178:181], v[102:105]
	v_mfma_f32_16x16x32_bf16 v[94:97], v[138:141], v[178:181], v[94:97]
	v_mfma_f32_16x16x32_bf16 v[86:89], v[130:133], v[208:211], v[86:89]
	v_mfma_f32_16x16x32_bf16 v[78:81], v[138:141], v[208:211], v[78:81]
	v_mfma_f32_16x16x32_bf16 v[126:129], v[134:137], v[166:169], v[126:129]
	v_mfma_f32_16x16x32_bf16 v[122:125], v[142:145], v[166:169], v[122:125]
	v_mfma_f32_16x16x32_bf16 v[118:121], v[134:137], v[174:177], v[118:121]
	v_mfma_f32_16x16x32_bf16 v[110:113], v[142:145], v[174:177], v[110:113]
	v_mfma_f32_16x16x32_bf16 v[102:105], v[134:137], v[204:207], v[102:105]
	v_mfma_f32_16x16x32_bf16 v[94:97], v[142:145], v[204:207], v[94:97]
	v_mfma_f32_16x16x32_bf16 v[86:89], v[134:137], v[212:215], v[86:89]
	v_mfma_f32_16x16x32_bf16 v[78:81], v[142:145], v[212:215], v[78:81]
	s_setprio 0
	s_setprio 1
	v_mfma_f32_16x16x32_bf16 v[114:117], v[146:149], v[162:165], v[114:117]
	v_mfma_f32_16x16x32_bf16 v[106:109], v[154:157], v[162:165], v[106:109]
	v_mfma_f32_16x16x32_bf16 v[98:101], v[146:149], v[170:173], v[98:101]
	v_mfma_f32_16x16x32_bf16 v[90:93], v[154:157], v[170:173], v[90:93]
	v_mfma_f32_16x16x32_bf16 v[82:85], v[146:149], v[178:181], v[82:85]
	v_mfma_f32_16x16x32_bf16 v[74:77], v[154:157], v[178:181], v[74:77]
	v_mfma_f32_16x16x32_bf16 v[70:73], v[146:149], v[208:211], v[70:73]
	v_mfma_f32_16x16x32_bf16 v[66:69], v[154:157], v[208:211], v[66:69]
	v_mfma_f32_16x16x32_bf16 v[114:117], v[150:153], v[166:169], v[114:117]
	v_mfma_f32_16x16x32_bf16 v[106:109], v[158:161], v[166:169], v[106:109]
	v_mfma_f32_16x16x32_bf16 v[98:101], v[150:153], v[174:177], v[98:101]
	v_mfma_f32_16x16x32_bf16 v[90:93], v[158:161], v[174:177], v[90:93]
	v_mfma_f32_16x16x32_bf16 v[82:85], v[150:153], v[204:207], v[82:85]
	v_mfma_f32_16x16x32_bf16 v[74:77], v[158:161], v[204:207], v[74:77]
	v_mfma_f32_16x16x32_bf16 v[70:73], v[150:153], v[212:215], v[70:73]
	v_mfma_f32_16x16x32_bf16 v[66:69], v[158:161], v[212:215], v[66:69]
	s_setprio 0
	s_barrier
	s_nop 0
	s_add_i32 s54, s45, s31
	v_lshl_add_u64 v[216:217], s[26:27], 0, v[186:187]
	s_mov_b32 m0, s54
	ds_read_b128 v[162:165], v202 offset:16384
	ds_read_b128 v[166:169], v202 offset:17408
	ds_read_b128 v[170:173], v202 offset:18432
	ds_read_b128 v[174:177], v202 offset:19456
	ds_read_b128 v[178:181], v202 offset:20480
	ds_read_b128 v[204:207], v202 offset:21504
	ds_read_b128 v[208:211], v202 offset:22528
	ds_read_b128 v[212:215], v202 offset:23552
	global_load_lds_dwordx4 v[216:217], off
	s_add_i32 m0, s54, 0x2000
	s_add_u32 s54, s26, 0x80000
	v_lshl_add_u64 v[218:219], s[26:27], 0, v[182:183]
	s_addc_u32 s55, s27, 0
	s_add_i32 s56, s46, s31
	global_load_lds_dwordx4 v[218:219], off
	v_lshl_add_u64 v[220:221], s[54:55], 0, v[186:187]
	s_mov_b32 m0, s56
	v_lshl_add_u64 v[222:223], s[28:29], 0, v[184:185]
	global_load_lds_dwordx4 v[220:221], off
	v_lshl_add_u64 v[220:221], s[54:55], 0, v[182:183]
	s_add_i32 m0, s56, 0x2000
	s_nop 0
	global_load_lds_dwordx4 v[220:221], off
	v_lshl_add_u64 v[220:221], s[28:29], 0, v[188:189]
	s_mov_b32 m0, s35
	s_nop 0
	global_load_lds_dwordx4 v[220:221], off
	s_mov_b32 m0, s36
	s_nop 0
	global_load_lds_dwordx4 v[222:223], off
	s_waitcnt vmcnt(8)
	s_waitcnt lgkmcnt(0)
	s_barrier
	s_setprio 1
	s_waitcnt lgkmcnt(0)
	v_mfma_f32_16x16x32_bf16 v[62:65], v[130:133], v[162:165], v[62:65]
	v_mfma_f32_16x16x32_bf16 v[58:61], v[138:141], v[162:165], v[58:61]
	v_mfma_f32_16x16x32_bf16 v[54:57], v[130:133], v[170:173], v[54:57]
	v_mfma_f32_16x16x32_bf16 v[46:49], v[138:141], v[170:173], v[46:49]
	v_mfma_f32_16x16x32_bf16 v[38:41], v[130:133], v[178:181], v[38:41]
	v_mfma_f32_16x16x32_bf16 v[30:33], v[138:141], v[178:181], v[30:33]
	v_mfma_f32_16x16x32_bf16 v[22:25], v[130:133], v[208:211], v[22:25]
	v_mfma_f32_16x16x32_bf16 v[14:17], v[138:141], v[208:211], v[14:17]
	v_mfma_f32_16x16x32_bf16 v[62:65], v[134:137], v[166:169], v[62:65]
	v_mfma_f32_16x16x32_bf16 v[58:61], v[142:145], v[166:169], v[58:61]
	v_mfma_f32_16x16x32_bf16 v[54:57], v[134:137], v[174:177], v[54:57]
	v_mfma_f32_16x16x32_bf16 v[46:49], v[142:145], v[174:177], v[46:49]
	v_mfma_f32_16x16x32_bf16 v[38:41], v[134:137], v[204:207], v[38:41]
	v_mfma_f32_16x16x32_bf16 v[30:33], v[142:145], v[204:207], v[30:33]
	v_mfma_f32_16x16x32_bf16 v[22:25], v[134:137], v[212:215], v[22:25]
	v_mfma_f32_16x16x32_bf16 v[14:17], v[142:145], v[212:215], v[14:17]
	s_setprio 0
	s_setprio 1
	v_mfma_f32_16x16x32_bf16 v[50:53], v[146:149], v[162:165], v[50:53]
	v_mfma_f32_16x16x32_bf16 v[42:45], v[154:157], v[162:165], v[42:45]
	v_mfma_f32_16x16x32_bf16 v[34:37], v[146:149], v[170:173], v[34:37]
	v_mfma_f32_16x16x32_bf16 v[26:29], v[154:157], v[170:173], v[26:29]
	v_mfma_f32_16x16x32_bf16 v[18:21], v[146:149], v[178:181], v[18:21]
	v_mfma_f32_16x16x32_bf16 v[10:13], v[154:157], v[178:181], v[10:13]
	v_mfma_f32_16x16x32_bf16 v[6:9], v[146:149], v[208:211], v[6:9]
	v_mfma_f32_16x16x32_bf16 v[2:5], v[154:157], v[208:211], v[2:5]
	v_mfma_f32_16x16x32_bf16 v[50:53], v[150:153], v[166:169], v[50:53]
	v_mfma_f32_16x16x32_bf16 v[42:45], v[158:161], v[166:169], v[42:45]
	v_mfma_f32_16x16x32_bf16 v[34:37], v[150:153], v[174:177], v[34:37]
	v_mfma_f32_16x16x32_bf16 v[26:29], v[158:161], v[174:177], v[26:29]
	v_mfma_f32_16x16x32_bf16 v[18:21], v[150:153], v[204:207], v[18:21]
	v_mfma_f32_16x16x32_bf16 v[10:13], v[158:161], v[204:207], v[10:13]
	v_mfma_f32_16x16x32_bf16 v[6:9], v[150:153], v[212:215], v[6:9]
	v_mfma_f32_16x16x32_bf16 v[2:5], v[158:161], v[212:215], v[2:5]
	s_setprio 0
	s_barrier
	s_nop 0
	s_add_i32 s54, 0, 0x18000
	s_add_i32 s55, 0, 0x1c000
	v_add_u32_e32 v142, s54, v199
	v_add_u32_e32 v158, s55, v199
	ds_read_b128 v[130:133], v142
	ds_read_b128 v[134:137], v142 offset:1024
	ds_read_b128 v[138:141], v142 offset:2048
	ds_read_b128 v[142:145], v142 offset:3072
	ds_read_b128 v[146:149], v158
	ds_read_b128 v[150:153], v158 offset:1024
	ds_read_b128 v[154:157], v158 offset:2048
	ds_read_b128 v[158:161], v158 offset:3072
	s_add_u32 s28, s28, 0x80000
	s_addc_u32 s29, s29, 0
	s_mov_b32 m0, s37
	v_lshl_add_u64 v[224:225], s[28:29], 0, v[188:189]
	ds_read_b128 v[162:165], v202 offset:32768
	ds_read_b128 v[166:169], v202 offset:33792
	ds_read_b128 v[170:173], v202 offset:34816
	ds_read_b128 v[174:177], v202 offset:35840
	ds_read_b128 v[178:181], v202 offset:36864
	ds_read_b128 v[204:207], v202 offset:37888
	ds_read_b128 v[208:211], v202 offset:38912
	ds_read_b128 v[212:215], v202 offset:39936
	global_load_lds_dwordx4 v[224:225], off
	v_lshl_add_u64 v[224:225], s[28:29], 0, v[184:185]
	s_mov_b32 m0, s38
	s_nop 0
	global_load_lds_dwordx4 v[224:225], off
	s_waitcnt vmcnt(8)
	s_waitcnt lgkmcnt(0)
	s_barrier
	s_setprio 1
	s_waitcnt lgkmcnt(0)
	v_mfma_f32_16x16x32_bf16 v[126:129], v[130:133], v[162:165], v[126:129]
	v_mfma_f32_16x16x32_bf16 v[122:125], v[138:141], v[162:165], v[122:125]
	v_mfma_f32_16x16x32_bf16 v[118:121], v[130:133], v[170:173], v[118:121]
	v_mfma_f32_16x16x32_bf16 v[110:113], v[138:141], v[170:173], v[110:113]
	v_mfma_f32_16x16x32_bf16 v[102:105], v[130:133], v[178:181], v[102:105]
	v_mfma_f32_16x16x32_bf16 v[94:97], v[138:141], v[178:181], v[94:97]
	v_mfma_f32_16x16x32_bf16 v[86:89], v[130:133], v[208:211], v[86:89]
	v_mfma_f32_16x16x32_bf16 v[78:81], v[138:141], v[208:211], v[78:81]
	v_mfma_f32_16x16x32_bf16 v[126:129], v[134:137], v[166:169], v[126:129]
	v_mfma_f32_16x16x32_bf16 v[122:125], v[142:145], v[166:169], v[122:125]
	v_mfma_f32_16x16x32_bf16 v[118:121], v[134:137], v[174:177], v[118:121]
	v_mfma_f32_16x16x32_bf16 v[110:113], v[142:145], v[174:177], v[110:113]
	v_mfma_f32_16x16x32_bf16 v[102:105], v[134:137], v[204:207], v[102:105]
	v_mfma_f32_16x16x32_bf16 v[94:97], v[142:145], v[204:207], v[94:97]
	v_mfma_f32_16x16x32_bf16 v[86:89], v[134:137], v[212:215], v[86:89]
	v_mfma_f32_16x16x32_bf16 v[78:81], v[142:145], v[212:215], v[78:81]
	s_setprio 0
	s_setprio 1
	v_mfma_f32_16x16x32_bf16 v[114:117], v[146:149], v[162:165], v[114:117]
	v_mfma_f32_16x16x32_bf16 v[106:109], v[154:157], v[162:165], v[106:109]
	v_mfma_f32_16x16x32_bf16 v[98:101], v[146:149], v[170:173], v[98:101]
	v_mfma_f32_16x16x32_bf16 v[90:93], v[154:157], v[170:173], v[90:93]
	v_mfma_f32_16x16x32_bf16 v[82:85], v[146:149], v[178:181], v[82:85]
	v_mfma_f32_16x16x32_bf16 v[74:77], v[154:157], v[178:181], v[74:77]
	v_mfma_f32_16x16x32_bf16 v[70:73], v[146:149], v[208:211], v[70:73]
	v_mfma_f32_16x16x32_bf16 v[66:69], v[154:157], v[208:211], v[66:69]
	v_mfma_f32_16x16x32_bf16 v[114:117], v[150:153], v[166:169], v[114:117]
	v_mfma_f32_16x16x32_bf16 v[106:109], v[158:161], v[166:169], v[106:109]
	v_mfma_f32_16x16x32_bf16 v[98:101], v[150:153], v[174:177], v[98:101]
	v_mfma_f32_16x16x32_bf16 v[90:93], v[158:161], v[174:177], v[90:93]
	v_mfma_f32_16x16x32_bf16 v[82:85], v[150:153], v[204:207], v[82:85]
	v_mfma_f32_16x16x32_bf16 v[74:77], v[158:161], v[204:207], v[74:77]
	v_mfma_f32_16x16x32_bf16 v[70:73], v[150:153], v[212:215], v[70:73]
	v_mfma_f32_16x16x32_bf16 v[66:69], v[158:161], v[212:215], v[66:69]
	s_setprio 0
	s_barrier
	s_add_i32 s28, s54, s31
	v_lshl_add_u64 v[216:217], v[216:217], 0, s[12:13]
	s_mov_b32 m0, s28
	ds_read_b128 v[162:165], v202 offset:49152
	ds_read_b128 v[166:169], v202 offset:50176
	ds_read_b128 v[170:173], v202 offset:51200
	ds_read_b128 v[174:177], v202 offset:52224
	ds_read_b128 v[178:181], v202 offset:53248
	ds_read_b128 v[204:207], v202 offset:54272
	ds_read_b128 v[208:211], v202 offset:55296
	ds_read_b128 v[212:215], v202 offset:56320
	global_load_lds_dwordx4 v[216:217], off
	s_add_i32 m0, s28, 0x2000
	s_add_u32 s26, s26, 0x80080
	v_lshl_add_u64 v[216:217], v[218:219], 0, s[12:13]
	s_addc_u32 s27, s27, 0
	s_add_i32 s28, s55, s31
	global_load_lds_dwordx4 v[216:217], off
	v_lshl_add_u64 v[216:217], s[26:27], 0, v[186:187]
	s_mov_b32 m0, s28
	s_nop 0
	global_load_lds_dwordx4 v[216:217], off
	v_lshl_add_u64 v[216:217], s[26:27], 0, v[182:183]
	s_add_i32 m0, s28, 0x2000
	s_nop 0
	global_load_lds_dwordx4 v[216:217], off
	v_lshl_add_u64 v[216:217], v[220:221], 0, s[12:13]
	s_mov_b32 m0, s42
	s_nop 0
	global_load_lds_dwordx4 v[216:217], off
	v_lshl_add_u64 v[216:217], v[222:223], 0, s[12:13]
	s_mov_b32 m0, s43
	s_nop 0
	global_load_lds_dwordx4 v[216:217], off
	s_waitcnt vmcnt(8)
	s_waitcnt lgkmcnt(0)
	s_barrier
	s_setprio 1
	s_waitcnt lgkmcnt(0)
	v_mfma_f32_16x16x32_bf16 v[62:65], v[130:133], v[162:165], v[62:65]
	v_mfma_f32_16x16x32_bf16 v[58:61], v[138:141], v[162:165], v[58:61]
	v_mfma_f32_16x16x32_bf16 v[54:57], v[130:133], v[170:173], v[54:57]
	v_mfma_f32_16x16x32_bf16 v[46:49], v[138:141], v[170:173], v[46:49]
	v_mfma_f32_16x16x32_bf16 v[38:41], v[130:133], v[178:181], v[38:41]
	v_mfma_f32_16x16x32_bf16 v[30:33], v[138:141], v[178:181], v[30:33]
	v_mfma_f32_16x16x32_bf16 v[22:25], v[130:133], v[208:211], v[22:25]
	v_mfma_f32_16x16x32_bf16 v[14:17], v[138:141], v[208:211], v[14:17]
	v_mfma_f32_16x16x32_bf16 v[62:65], v[134:137], v[166:169], v[62:65]
	v_mfma_f32_16x16x32_bf16 v[58:61], v[142:145], v[166:169], v[58:61]
	v_mfma_f32_16x16x32_bf16 v[54:57], v[134:137], v[174:177], v[54:57]
	v_mfma_f32_16x16x32_bf16 v[46:49], v[142:145], v[174:177], v[46:49]
	v_mfma_f32_16x16x32_bf16 v[38:41], v[134:137], v[204:207], v[38:41]
	v_mfma_f32_16x16x32_bf16 v[30:33], v[142:145], v[204:207], v[30:33]
	v_mfma_f32_16x16x32_bf16 v[22:25], v[134:137], v[212:215], v[22:25]
	v_mfma_f32_16x16x32_bf16 v[14:17], v[142:145], v[212:215], v[14:17]
	s_setprio 0
	s_setprio 1
	v_mfma_f32_16x16x32_bf16 v[50:53], v[146:149], v[162:165], v[50:53]
	v_mfma_f32_16x16x32_bf16 v[42:45], v[154:157], v[162:165], v[42:45]
	v_mfma_f32_16x16x32_bf16 v[34:37], v[146:149], v[170:173], v[34:37]
	v_mfma_f32_16x16x32_bf16 v[26:29], v[154:157], v[170:173], v[26:29]
	v_mfma_f32_16x16x32_bf16 v[18:21], v[146:149], v[178:181], v[18:21]
	v_mfma_f32_16x16x32_bf16 v[10:13], v[154:157], v[178:181], v[10:13]
	v_mfma_f32_16x16x32_bf16 v[6:9], v[146:149], v[208:211], v[6:9]
	v_mfma_f32_16x16x32_bf16 v[2:5], v[154:157], v[208:211], v[2:5]
	v_mfma_f32_16x16x32_bf16 v[50:53], v[150:153], v[166:169], v[50:53]
	v_mfma_f32_16x16x32_bf16 v[42:45], v[158:161], v[166:169], v[42:45]
	v_mfma_f32_16x16x32_bf16 v[34:37], v[150:153], v[174:177], v[34:37]
	v_mfma_f32_16x16x32_bf16 v[26:29], v[158:161], v[174:177], v[26:29]
	v_mfma_f32_16x16x32_bf16 v[18:21], v[150:153], v[204:207], v[18:21]
	v_mfma_f32_16x16x32_bf16 v[10:13], v[158:161], v[204:207], v[10:13]
	v_mfma_f32_16x16x32_bf16 v[6:9], v[150:153], v[212:215], v[6:9]
	v_mfma_f32_16x16x32_bf16 v[2:5], v[158:161], v[212:215], v[2:5]
	s_setprio 0
	s_barrier
	s_add_i32 s53, s53, 2
	s_add_u32 s8, s8, 0x100
	s_addc_u32 s9, s9, 0
	s_add_u32 s51, s51, 0x100
	s_addc_u32 s52, s52, 0
	s_cmp_gt_u32 s53, 29
	s_cbranch_scc0 .LBB0_1942
	s_and_b64 vcc, exec, s[14:15]
	s_cbranch_vccz .LBB0_1945
	s_barrier

.LBB0_3201:
	ds_read_b128 v[146:149], v164
	s_waitcnt lgkmcnt(0)
	ds_read_b128 v[150:153], v164 offset:1024
	ds_read_b128 v[154:157], v164 offset:2048
	ds_read_b128 v[158:161], v164 offset:3072
	ds_read_b128 v[168:171], v165
	ds_read_b128 v[172:175], v165 offset:1024
	ds_read_b128 v[176:179], v165 offset:2048
	ds_read_b128 v[180:183], v165 offset:3072
	s_add_u32 s40, s8, 0xfff80080
	s_addc_u32 s41, s9, -1
	s_cmp_eq_u32 s66, 28
	s_cselect_b32 s43, s7, s41
	s_cselect_b32 s42, s35, s40
	s_cselect_b32 s41, s31, s65
	s_cselect_b32 s40, s63, s64
	v_lshl_add_u64 v[216:217], s[8:9], 0, v[138:139]
	s_add_i32 m0, s46, 0xc000
	ds_read_b128 v[184:187], v166
	ds_read_b128 v[188:191], v166 offset:1024
	ds_read_b128 v[192:195], v166 offset:2048
	ds_read_b128 v[196:199], v166 offset:3072
	ds_read_b128 v[200:203], v166 offset:4096
	ds_read_b128 v[204:207], v166 offset:5120
	ds_read_b128 v[208:211], v166 offset:6144
	ds_read_b128 v[212:215], v166 offset:7168
	global_load_lds_dwordx4 v[216:217], off
	v_lshl_add_u64 v[216:217], s[8:9], 0, v[140:141]
	s_add_i32 m0, s46, 0xe000
	s_nop 0
	global_load_lds_dwordx4 v[216:217], off
	s_waitcnt vmcnt(8)
	s_waitcnt lgkmcnt(0)
	s_barrier
	s_setprio 1
	s_waitcnt lgkmcnt(0)
	v_mfma_f32_16x16x32_bf16 v[126:129], v[146:149], v[184:187], v[126:129]
	v_mfma_f32_16x16x32_bf16 v[122:125], v[154:157], v[184:187], v[122:125]
	v_mfma_f32_16x16x32_bf16 v[118:121], v[146:149], v[192:195], v[118:121]
	v_mfma_f32_16x16x32_bf16 v[110:113], v[154:157], v[192:195], v[110:113]
	v_mfma_f32_16x16x32_bf16 v[102:105], v[146:149], v[200:203], v[102:105]
	v_mfma_f32_16x16x32_bf16 v[94:97], v[154:157], v[200:203], v[94:97]
	v_mfma_f32_16x16x32_bf16 v[86:89], v[146:149], v[208:211], v[86:89]
	v_mfma_f32_16x16x32_bf16 v[78:81], v[154:157], v[208:211], v[78:81]
	v_mfma_f32_16x16x32_bf16 v[126:129], v[150:153], v[188:191], v[126:129]
	v_mfma_f32_16x16x32_bf16 v[122:125], v[158:161], v[188:191], v[122:125]
	v_mfma_f32_16x16x32_bf16 v[118:121], v[150:153], v[196:199], v[118:121]
	v_mfma_f32_16x16x32_bf16 v[110:113], v[158:161], v[196:199], v[110:113]
	v_mfma_f32_16x16x32_bf16 v[102:105], v[150:153], v[204:207], v[102:105]
	v_mfma_f32_16x16x32_bf16 v[94:97], v[158:161], v[204:207], v[94:97]
	v_mfma_f32_16x16x32_bf16 v[86:89], v[150:153], v[212:215], v[86:89]
	v_mfma_f32_16x16x32_bf16 v[78:81], v[158:161], v[212:215], v[78:81]
	s_setprio 0
	s_setprio 1
	v_mfma_f32_16x16x32_bf16 v[114:117], v[168:171], v[184:187], v[114:117]
	v_mfma_f32_16x16x32_bf16 v[106:109], v[176:179], v[184:187], v[106:109]
	v_mfma_f32_16x16x32_bf16 v[98:101], v[168:171], v[192:195], v[98:101]
	v_mfma_f32_16x16x32_bf16 v[90:93], v[176:179], v[192:195], v[90:93]
	v_mfma_f32_16x16x32_bf16 v[82:85], v[168:171], v[200:203], v[82:85]
	v_mfma_f32_16x16x32_bf16 v[74:77], v[176:179], v[200:203], v[74:77]
	v_mfma_f32_16x16x32_bf16 v[70:73], v[168:171], v[208:211], v[70:73]
	v_mfma_f32_16x16x32_bf16 v[66:69], v[176:179], v[208:211], v[66:69]
	v_mfma_f32_16x16x32_bf16 v[114:117], v[172:175], v[188:191], v[114:117]
	v_mfma_f32_16x16x32_bf16 v[106:109], v[180:183], v[188:191], v[106:109]
	v_mfma_f32_16x16x32_bf16 v[98:101], v[172:175], v[196:199], v[98:101]
	v_mfma_f32_16x16x32_bf16 v[90:93], v[180:183], v[196:199], v[90:93]
	v_mfma_f32_16x16x32_bf16 v[82:85], v[172:175], v[204:207], v[82:85]
	v_mfma_f32_16x16x32_bf16 v[74:77], v[180:183], v[204:207], v[74:77]
	v_mfma_f32_16x16x32_bf16 v[70:73], v[172:175], v[212:215], v[70:73]
	v_mfma_f32_16x16x32_bf16 v[66:69], v[180:183], v[212:215], v[66:69]
	s_setprio 0
	s_barrier
	s_nop 0
	s_add_i32 s67, s56, s33
	v_lshl_add_u64 v[216:217], s[40:41], 0, v[134:135]
	s_mov_b32 m0, s67
	ds_read_b128 v[184:187], v166 offset:16384
	ds_read_b128 v[188:191], v166 offset:17408
	ds_read_b128 v[192:195], v166 offset:18432
	ds_read_b128 v[196:199], v166 offset:19456
	ds_read_b128 v[200:203], v166 offset:20480
	ds_read_b128 v[204:207], v166 offset:21504
	ds_read_b128 v[208:211], v166 offset:22528
	ds_read_b128 v[212:215], v166 offset:23552
	global_load_lds_dwordx4 v[216:217], off
	s_add_i32 m0, s67, 0x2000
	s_add_u32 s68, s40, 0x80000
	v_lshl_add_u64 v[218:219], s[40:41], 0, v[130:131]
	s_addc_u32 s69, s41, 0
	s_add_i32 s67, s57, s33
	global_load_lds_dwordx4 v[218:219], off
	v_lshl_add_u64 v[220:221], s[68:69], 0, v[134:135]
	s_mov_b32 m0, s67
	v_lshl_add_u64 v[222:223], s[42:43], 0, v[132:133]
	global_load_lds_dwordx4 v[220:221], off
	v_lshl_add_u64 v[220:221], s[68:69], 0, v[130:131]
	s_add_i32 m0, s67, 0x2000
	s_nop 0
	global_load_lds_dwordx4 v[220:221], off
	v_lshl_add_u64 v[220:221], s[42:43], 0, v[136:137]
	s_mov_b32 m0, s46
	s_nop 0
	global_load_lds_dwordx4 v[220:221], off
	s_mov_b32 m0, s47
	s_nop 0
	global_load_lds_dwordx4 v[222:223], off
	s_waitcnt vmcnt(8)
	s_waitcnt lgkmcnt(0)
	s_barrier
	s_setprio 1
	s_waitcnt lgkmcnt(0)
	v_mfma_f32_16x16x32_bf16 v[62:65], v[146:149], v[184:187], v[62:65]
	v_mfma_f32_16x16x32_bf16 v[58:61], v[154:157], v[184:187], v[58:61]
	v_mfma_f32_16x16x32_bf16 v[54:57], v[146:149], v[192:195], v[54:57]
	v_mfma_f32_16x16x32_bf16 v[46:49], v[154:157], v[192:195], v[46:49]
	v_mfma_f32_16x16x32_bf16 v[38:41], v[146:149], v[200:203], v[38:41]
	v_mfma_f32_16x16x32_bf16 v[30:33], v[154:157], v[200:203], v[30:33]
	v_mfma_f32_16x16x32_bf16 v[22:25], v[146:149], v[208:211], v[22:25]
	v_mfma_f32_16x16x32_bf16 v[14:17], v[154:157], v[208:211], v[14:17]
	v_mfma_f32_16x16x32_bf16 v[62:65], v[150:153], v[188:191], v[62:65]
	v_mfma_f32_16x16x32_bf16 v[58:61], v[158:161], v[188:191], v[58:61]
	v_mfma_f32_16x16x32_bf16 v[54:57], v[150:153], v[196:199], v[54:57]
	v_mfma_f32_16x16x32_bf16 v[46:49], v[158:161], v[196:199], v[46:49]
	v_mfma_f32_16x16x32_bf16 v[38:41], v[150:153], v[204:207], v[38:41]
	v_mfma_f32_16x16x32_bf16 v[30:33], v[158:161], v[204:207], v[30:33]
	v_mfma_f32_16x16x32_bf16 v[22:25], v[150:153], v[212:215], v[22:25]
	v_mfma_f32_16x16x32_bf16 v[14:17], v[158:161], v[212:215], v[14:17]
	s_setprio 0
	s_setprio 1
	v_mfma_f32_16x16x32_bf16 v[50:53], v[168:171], v[184:187], v[50:53]
	v_mfma_f32_16x16x32_bf16 v[42:45], v[176:179], v[184:187], v[42:45]
	v_mfma_f32_16x16x32_bf16 v[34:37], v[168:171], v[192:195], v[34:37]
	v_mfma_f32_16x16x32_bf16 v[26:29], v[176:179], v[192:195], v[26:29]
	v_mfma_f32_16x16x32_bf16 v[18:21], v[168:171], v[200:203], v[18:21]
	v_mfma_f32_16x16x32_bf16 v[10:13], v[176:179], v[200:203], v[10:13]
	v_mfma_f32_16x16x32_bf16 v[6:9], v[168:171], v[208:211], v[6:9]
	v_mfma_f32_16x16x32_bf16 v[2:5], v[176:179], v[208:211], v[2:5]
	v_mfma_f32_16x16x32_bf16 v[50:53], v[172:175], v[188:191], v[50:53]
	v_mfma_f32_16x16x32_bf16 v[42:45], v[180:183], v[188:191], v[42:45]
	v_mfma_f32_16x16x32_bf16 v[34:37], v[172:175], v[196:199], v[34:37]
	v_mfma_f32_16x16x32_bf16 v[26:29], v[180:183], v[196:199], v[26:29]
	v_mfma_f32_16x16x32_bf16 v[18:21], v[172:175], v[204:207], v[18:21]
	v_mfma_f32_16x16x32_bf16 v[10:13], v[180:183], v[204:207], v[10:13]
	v_mfma_f32_16x16x32_bf16 v[6:9], v[172:175], v[212:215], v[6:9]
	v_mfma_f32_16x16x32_bf16 v[2:5], v[180:183], v[212:215], v[2:5]
	s_setprio 0
	s_barrier
	s_nop 0
	s_add_i32 s67, 0, 0x18000
	s_add_i32 s68, 0, 0x1c000
	v_add_u32_e32 v158, s67, v163
	v_add_u32_e32 v180, s68, v163
	ds_read_b128 v[146:149], v158
	ds_read_b128 v[150:153], v158 offset:1024
	ds_read_b128 v[154:157], v158 offset:2048
	ds_read_b128 v[158:161], v158 offset:3072
	ds_read_b128 v[168:171], v180
	ds_read_b128 v[172:175], v180 offset:1024
	ds_read_b128 v[176:179], v180 offset:2048
	ds_read_b128 v[180:183], v180 offset:3072
	s_add_u32 s42, s42, 0x80000
	s_addc_u32 s43, s43, 0
	s_mov_b32 m0, s48
	v_lshl_add_u64 v[224:225], s[42:43], 0, v[136:137]
	ds_read_b128 v[184:187], v166 offset:32768
	ds_read_b128 v[188:191], v166 offset:33792
	ds_read_b128 v[192:195], v166 offset:34816
	ds_read_b128 v[196:199], v166 offset:35840
	ds_read_b128 v[200:203], v166 offset:36864
	ds_read_b128 v[204:207], v166 offset:37888
	ds_read_b128 v[208:211], v166 offset:38912
	ds_read_b128 v[212:215], v166 offset:39936
	global_load_lds_dwordx4 v[224:225], off
	v_lshl_add_u64 v[224:225], s[42:43], 0, v[132:133]
	s_mov_b32 m0, s49
	s_nop 0
	global_load_lds_dwordx4 v[224:225], off
	s_waitcnt vmcnt(8)
	s_waitcnt lgkmcnt(0)
	s_barrier
	s_setprio 1
	s_waitcnt lgkmcnt(0)
	v_mfma_f32_16x16x32_bf16 v[126:129], v[146:149], v[184:187], v[126:129]
	v_mfma_f32_16x16x32_bf16 v[122:125], v[154:157], v[184:187], v[122:125]
	v_mfma_f32_16x16x32_bf16 v[118:121], v[146:149], v[192:195], v[118:121]
	v_mfma_f32_16x16x32_bf16 v[110:113], v[154:157], v[192:195], v[110:113]
	v_mfma_f32_16x16x32_bf16 v[102:105], v[146:149], v[200:203], v[102:105]
	v_mfma_f32_16x16x32_bf16 v[94:97], v[154:157], v[200:203], v[94:97]
	v_mfma_f32_16x16x32_bf16 v[86:89], v[146:149], v[208:211], v[86:89]
	v_mfma_f32_16x16x32_bf16 v[78:81], v[154:157], v[208:211], v[78:81]
	v_mfma_f32_16x16x32_bf16 v[126:129], v[150:153], v[188:191], v[126:129]
	v_mfma_f32_16x16x32_bf16 v[122:125], v[158:161], v[188:191], v[122:125]
	v_mfma_f32_16x16x32_bf16 v[118:121], v[150:153], v[196:199], v[118:121]
	v_mfma_f32_16x16x32_bf16 v[110:113], v[158:161], v[196:199], v[110:113]
	v_mfma_f32_16x16x32_bf16 v[102:105], v[150:153], v[204:207], v[102:105]
	v_mfma_f32_16x16x32_bf16 v[94:97], v[158:161], v[204:207], v[94:97]
	v_mfma_f32_16x16x32_bf16 v[86:89], v[150:153], v[212:215], v[86:89]
	v_mfma_f32_16x16x32_bf16 v[78:81], v[158:161], v[212:215], v[78:81]
	s_setprio 0
	s_setprio 1
	v_mfma_f32_16x16x32_bf16 v[114:117], v[168:171], v[184:187], v[114:117]
	v_mfma_f32_16x16x32_bf16 v[106:109], v[176:179], v[184:187], v[106:109]
	v_mfma_f32_16x16x32_bf16 v[98:101], v[168:171], v[192:195], v[98:101]
	v_mfma_f32_16x16x32_bf16 v[90:93], v[176:179], v[192:195], v[90:93]
	v_mfma_f32_16x16x32_bf16 v[82:85], v[168:171], v[200:203], v[82:85]
	v_mfma_f32_16x16x32_bf16 v[74:77], v[176:179], v[200:203], v[74:77]
	v_mfma_f32_16x16x32_bf16 v[70:73], v[168:171], v[208:211], v[70:73]
	v_mfma_f32_16x16x32_bf16 v[66:69], v[176:179], v[208:211], v[66:69]
	v_mfma_f32_16x16x32_bf16 v[114:117], v[172:175], v[188:191], v[114:117]
	v_mfma_f32_16x16x32_bf16 v[106:109], v[180:183], v[188:191], v[106:109]
	v_mfma_f32_16x16x32_bf16 v[98:101], v[172:175], v[196:199], v[98:101]
	v_mfma_f32_16x16x32_bf16 v[90:93], v[180:183], v[196:199], v[90:93]
	v_mfma_f32_16x16x32_bf16 v[82:85], v[172:175], v[204:207], v[82:85]
	v_mfma_f32_16x16x32_bf16 v[74:77], v[180:183], v[204:207], v[74:77]
	v_mfma_f32_16x16x32_bf16 v[70:73], v[172:175], v[212:215], v[70:73]
	v_mfma_f32_16x16x32_bf16 v[66:69], v[180:183], v[212:215], v[66:69]
	s_setprio 0
	s_barrier
	s_add_i32 s42, s67, s33
	v_lshl_add_u64 v[216:217], v[216:217], 0, s[12:13]
	s_mov_b32 m0, s42
	ds_read_b128 v[184:187], v166 offset:49152
	ds_read_b128 v[188:191], v166 offset:50176
	ds_read_b128 v[192:195], v166 offset:51200
	ds_read_b128 v[196:199], v166 offset:52224
	ds_read_b128 v[200:203], v166 offset:53248
	ds_read_b128 v[204:207], v166 offset:54272
	ds_read_b128 v[208:211], v166 offset:55296
	ds_read_b128 v[212:215], v166 offset:56320
	global_load_lds_dwordx4 v[216:217], off
	s_add_i32 m0, s42, 0x2000
	s_add_u32 s40, s40, 0x80080
	v_lshl_add_u64 v[216:217], v[218:219], 0, s[12:13]
	s_addc_u32 s41, s41, 0
	s_add_i32 s42, s68, s33
	global_load_lds_dwordx4 v[216:217], off
	v_lshl_add_u64 v[216:217], s[40:41], 0, v[134:135]
	s_mov_b32 m0, s42
	s_nop 0
	global_load_lds_dwordx4 v[216:217], off
	v_lshl_add_u64 v[216:217], s[40:41], 0, v[130:131]
	s_add_i32 m0, s42, 0x2000
	s_nop 0
	global_load_lds_dwordx4 v[216:217], off
	v_lshl_add_u64 v[216:217], v[220:221], 0, s[12:13]
	s_mov_b32 m0, s53
	s_nop 0
	global_load_lds_dwordx4 v[216:217], off
	v_lshl_add_u64 v[216:217], v[222:223], 0, s[12:13]
	s_mov_b32 m0, s54
	s_nop 0
	global_load_lds_dwordx4 v[216:217], off
	s_waitcnt vmcnt(8)
	s_waitcnt lgkmcnt(0)
	s_barrier
	s_setprio 1
	s_waitcnt lgkmcnt(0)
	v_mfma_f32_16x16x32_bf16 v[62:65], v[146:149], v[184:187], v[62:65]
	v_mfma_f32_16x16x32_bf16 v[58:61], v[154:157], v[184:187], v[58:61]
	v_mfma_f32_16x16x32_bf16 v[54:57], v[146:149], v[192:195], v[54:57]
	v_mfma_f32_16x16x32_bf16 v[46:49], v[154:157], v[192:195], v[46:49]
	v_mfma_f32_16x16x32_bf16 v[38:41], v[146:149], v[200:203], v[38:41]
	v_mfma_f32_16x16x32_bf16 v[30:33], v[154:157], v[200:203], v[30:33]
	v_mfma_f32_16x16x32_bf16 v[22:25], v[146:149], v[208:211], v[22:25]
	v_mfma_f32_16x16x32_bf16 v[14:17], v[154:157], v[208:211], v[14:17]
	v_mfma_f32_16x16x32_bf16 v[62:65], v[150:153], v[188:191], v[62:65]
	v_mfma_f32_16x16x32_bf16 v[58:61], v[158:161], v[188:191], v[58:61]
	v_mfma_f32_16x16x32_bf16 v[54:57], v[150:153], v[196:199], v[54:57]
	v_mfma_f32_16x16x32_bf16 v[46:49], v[158:161], v[196:199], v[46:49]
	v_mfma_f32_16x16x32_bf16 v[38:41], v[150:153], v[204:207], v[38:41]
	v_mfma_f32_16x16x32_bf16 v[30:33], v[158:161], v[204:207], v[30:33]
	v_mfma_f32_16x16x32_bf16 v[22:25], v[150:153], v[212:215], v[22:25]
	v_mfma_f32_16x16x32_bf16 v[14:17], v[158:161], v[212:215], v[14:17]
	s_setprio 0
	s_setprio 1
	v_mfma_f32_16x16x32_bf16 v[50:53], v[168:171], v[184:187], v[50:53]
	v_mfma_f32_16x16x32_bf16 v[42:45], v[176:179], v[184:187], v[42:45]
	v_mfma_f32_16x16x32_bf16 v[34:37], v[168:171], v[192:195], v[34:37]
	v_mfma_f32_16x16x32_bf16 v[26:29], v[176:179], v[192:195], v[26:29]
	v_mfma_f32_16x16x32_bf16 v[18:21], v[168:171], v[200:203], v[18:21]
	v_mfma_f32_16x16x32_bf16 v[10:13], v[176:179], v[200:203], v[10:13]
	v_mfma_f32_16x16x32_bf16 v[6:9], v[168:171], v[208:211], v[6:9]
	v_mfma_f32_16x16x32_bf16 v[2:5], v[176:179], v[208:211], v[2:5]
	v_mfma_f32_16x16x32_bf16 v[50:53], v[172:175], v[188:191], v[50:53]
	v_mfma_f32_16x16x32_bf16 v[42:45], v[180:183], v[188:191], v[42:45]
	v_mfma_f32_16x16x32_bf16 v[34:37], v[172:175], v[196:199], v[34:37]
	v_mfma_f32_16x16x32_bf16 v[26:29], v[180:183], v[196:199], v[26:29]
	v_mfma_f32_16x16x32_bf16 v[18:21], v[172:175], v[204:207], v[18:21]
	v_mfma_f32_16x16x32_bf16 v[10:13], v[180:183], v[204:207], v[10:13]
	v_mfma_f32_16x16x32_bf16 v[6:9], v[172:175], v[212:215], v[6:9]
	v_mfma_f32_16x16x32_bf16 v[2:5], v[180:183], v[212:215], v[2:5]
	s_setprio 0
	s_barrier
	s_add_i32 s66, s66, 2
	s_add_u32 s8, s8, 0x100
	s_addc_u32 s9, s9, 0
	s_add_u32 s64, s64, 0x100
	s_addc_u32 s65, s65, 0
	s_cmp_gt_u32 s66, 29
	s_cbranch_scc0 .LBB0_3201
	s_and_b64 vcc, exec, s[14:15]
	s_cbranch_vccz .LBB0_3204
	s_barrier
